# P2 epilogue stores sc1 instead of nt
# baseline (speedup 1.0000x reference)
; __device__ __forceinline__ unsigned cvt_pk_bf16(float lo, float hi) { unsigned r; asm volatile("v_cvt_pk_bf16_f32 %0, %1, %2" : "=v"(r) : "v"(lo), "v"(hi)); return r; }
;     __device__ __forceinline__ void operator()(const f32x4 (&acc)[2][2][4][2], const Unit& u, int wr, int wc, int fr, int fq) const {
;     ...
;             bf16_t* base; int ld, ct; float sc = 1.f;
;             if (pn < 4) { base = Q; ld = 1024; ct = pn; sc = qscale; } else if (pn < 8) { base = Kb; ld = 1024; ct = pn - 4; } else if (pn < 12) { base = V; ld = 1024; ct = pn - 8; }
;             else if (pn < 14) { base = U; ld = 512; ct = pn - 12; } else { base = G; ld = 2048; ct = pn - 14; }
;             const int row0 = u.pm * BM + wr * 64 + fr, col0 = ct * 256 + wc * 32 + 8 * fq;
; #pragma unroll
;             for (int ai = 0; ai < 2; ++ai)
; #pragma unroll
;                 for (int m = 0; m < 4; ++m) { bf16_t* rowp = base + (size_t)(row0 + ai * HALF + m * 16) * ld + col0;
; #pragma unroll
;                     for (int bj = 0; bj < 2; ++bj) { const f32x4 v0 = acc[ai][bj][m][0] * sc, v1 = acc[ai][bj][m][1] * sc;
;                         u32x4 w; w.x = cvt_pk_bf16(v0[0], v0[1]); w.y = cvt_pk_bf16(v0[2], v0[3]); w.z = cvt_pk_bf16(v1[0], v1[1]); w.w = cvt_pk_bf16(v1[2], v1[3]);
;                         __builtin_nontemporal_store(w, (u32x4*)(rowp + bj * HALF)); } }
.LBB0_215:
	s_cmp_lt_u32 s73, 14
	s_cselect_b64 s[60:61], -1, 0
	s_and_b64 s[66:67], s[60:61], exec
	s_cselect_b32 s13, -12, -14
	s_add_i32 s13, s13, s73
	s_and_b64 s[60:61], s[60:61], exec
	s_cselect_b32 s15, s1, s21
	s_cselect_b32 s33, s0, s20
	v_lshl_add_u32 v148, s58, 8, v150
	v_mov_b32_e32 v146, s33
	s_waitcnt lgkmcnt(0)
	v_mov_b32_e32 v147, s15
	v_lshl_or_b32 v162, s13, 8, v158
	v_mov_b32_e32 v163, v137
	v_ashrrev_i32_e32 v149, 31, v148
	s_cselect_b32 s13, 9, 11
	v_lshl_add_u64 v[146:147], v[162:163], 1, v[146:147]
	v_lshlrev_b64 v[162:163], s13, v[148:149]
	v_lshl_add_u64 v[166:167], v[162:163], 1, v[146:147]
	v_cvt_pk_bf16_f32 v162, v124, v125
	v_cvt_pk_bf16_f32 v163, v126, v127
	v_cvt_pk_bf16_f32 v164, v120, v121
	v_cvt_pk_bf16_f32 v165, v122, v123
	global_store_dwordx4 v[166:167], v[162:165], off sc1
	s_nop 1
	v_cvt_pk_bf16_f32 v162, v68, v69
	v_cvt_pk_bf16_f32 v163, v70, v71
	v_cvt_pk_bf16_f32 v164, v64, v65
	v_cvt_pk_bf16_f32 v165, v66, v67
	global_store_dwordx4 v[166:167], v[162:165], off offset:256 sc1
	s_nop 1
	v_or_b32_e32 v162, 16, v148
	v_ashrrev_i32_e32 v163, 31, v162
	v_lshlrev_b64 v[162:163], s13, v[162:163]
	v_lshl_add_u64 v[166:167], v[162:163], 1, v[146:147]
	v_cvt_pk_bf16_f32 v162, v116, v117
	v_cvt_pk_bf16_f32 v163, v118, v119
	v_cvt_pk_bf16_f32 v164, v112, v113
	v_cvt_pk_bf16_f32 v165, v114, v115
	global_store_dwordx4 v[166:167], v[162:165], off sc1
	s_nop 1
	v_cvt_pk_bf16_f32 v162, v56, v57
	v_cvt_pk_bf16_f32 v163, v58, v59
	v_cvt_pk_bf16_f32 v164, v48, v49
	v_cvt_pk_bf16_f32 v165, v50, v51
	global_store_dwordx4 v[166:167], v[162:165], off offset:256 sc1
	s_nop 1
	v_or_b32_e32 v162, 32, v148
	v_ashrrev_i32_e32 v163, 31, v162
	v_lshlrev_b64 v[162:163], s13, v[162:163]
	v_lshl_add_u64 v[166:167], v[162:163], 1, v[146:147]
	v_cvt_pk_bf16_f32 v162, v108, v109
	v_cvt_pk_bf16_f32 v163, v110, v111
	v_cvt_pk_bf16_f32 v164, v104, v105
	v_cvt_pk_bf16_f32 v165, v106, v107
	global_store_dwordx4 v[166:167], v[162:165], off sc1
	s_nop 1
	v_cvt_pk_bf16_f32 v162, v44, v45
	v_cvt_pk_bf16_f32 v163, v46, v47
	v_cvt_pk_bf16_f32 v164, v40, v41
	v_cvt_pk_bf16_f32 v165, v42, v43
	global_store_dwordx4 v[166:167], v[162:165], off offset:256 sc1
	s_nop 1
	v_or_b32_e32 v162, 48, v148
	v_ashrrev_i32_e32 v163, 31, v162
	v_lshlrev_b64 v[162:163], s13, v[162:163]
	v_lshl_add_u64 v[166:167], v[162:163], 1, v[146:147]
	v_cvt_pk_bf16_f32 v162, v100, v101
	v_cvt_pk_bf16_f32 v163, v102, v103
	v_cvt_pk_bf16_f32 v164, v96, v97
	v_cvt_pk_bf16_f32 v165, v98, v99
	global_store_dwordx4 v[166:167], v[162:165], off sc1
	s_nop 1
	v_cvt_pk_bf16_f32 v162, v36, v37
	v_cvt_pk_bf16_f32 v163, v38, v39
	v_cvt_pk_bf16_f32 v164, v32, v33
	v_cvt_pk_bf16_f32 v165, v34, v35
	global_store_dwordx4 v[166:167], v[162:165], off offset:256 sc1
	s_nop 1
	v_add_u32_e32 v162, 0x80, v148
	v_ashrrev_i32_e32 v163, 31, v162
	v_lshlrev_b64 v[162:163], s13, v[162:163]
	v_lshl_add_u64 v[166:167], v[162:163], 1, v[146:147]
	v_cvt_pk_bf16_f32 v162, v92, v93
	v_cvt_pk_bf16_f32 v163, v94, v95
	v_cvt_pk_bf16_f32 v164, v88, v89
	v_cvt_pk_bf16_f32 v165, v90, v91
	global_store_dwordx4 v[166:167], v[162:165], off sc1
	s_nop 1
	v_cvt_pk_bf16_f32 v162, v28, v29
	v_cvt_pk_bf16_f32 v163, v30, v31
	v_cvt_pk_bf16_f32 v164, v24, v25
	v_cvt_pk_bf16_f32 v165, v26, v27
	global_store_dwordx4 v[166:167], v[162:165], off offset:256 sc1
	s_nop 1
	v_add_u32_e32 v162, 0x90, v148
	v_ashrrev_i32_e32 v163, 31, v162
	v_lshlrev_b64 v[162:163], s13, v[162:163]
	v_lshl_add_u64 v[166:167], v[162:163], 1, v[146:147]
	v_cvt_pk_bf16_f32 v162, v84, v85
	v_cvt_pk_bf16_f32 v163, v86, v87
	v_cvt_pk_bf16_f32 v164, v80, v81
	v_cvt_pk_bf16_f32 v165, v82, v83
	global_store_dwordx4 v[166:167], v[162:165], off sc1
	s_nop 1
	v_cvt_pk_bf16_f32 v162, v20, v21
	v_cvt_pk_bf16_f32 v163, v22, v23
	v_cvt_pk_bf16_f32 v164, v16, v17
	v_cvt_pk_bf16_f32 v165, v18, v19
	global_store_dwordx4 v[166:167], v[162:165], off offset:256 sc1
	s_nop 1
	v_add_u32_e32 v162, 0xa0, v148
	v_ashrrev_i32_e32 v163, 31, v162
	v_lshlrev_b64 v[162:163], s13, v[162:163]
	v_add_u32_e32 v148, 0xb0, v148
	v_lshl_add_u64 v[166:167], v[162:163], 1, v[146:147]
	v_cvt_pk_bf16_f32 v162, v76, v77
	v_cvt_pk_bf16_f32 v163, v78, v79
	v_ashrrev_i32_e32 v149, 31, v148
	v_cvt_pk_bf16_f32 v164, v72, v73
	v_cvt_pk_bf16_f32 v165, v74, v75
	global_store_dwordx4 v[166:167], v[162:165], off sc1
	v_lshlrev_b64 v[148:149], s13, v[148:149]
	s_nop 0
	v_cvt_pk_bf16_f32 v162, v12, v13
	v_cvt_pk_bf16_f32 v163, v14, v15
	v_cvt_pk_bf16_f32 v164, v8, v9
	v_cvt_pk_bf16_f32 v165, v10, v11
	global_store_dwordx4 v[166:167], v[162:165], off offset:256 sc1
	s_nop 1
	v_lshl_add_u64 v[162:163], v[148:149], 1, v[146:147]
	v_cvt_pk_bf16_f32 v146, v60, v61
	v_cvt_pk_bf16_f32 v147, v62, v63
	v_cvt_pk_bf16_f32 v148, v52, v53
	v_cvt_pk_bf16_f32 v149, v54, v55
	global_store_dwordx4 v[162:163], v[146:149], off sc1
	s_nop 1
	v_cvt_pk_bf16_f32 v146, v4, v5
	v_cvt_pk_bf16_f32 v147, v6, v7
	v_cvt_pk_bf16_f32 v148, v0, v1
	v_cvt_pk_bf16_f32 v149, v2, v3
	global_store_dwordx4 v[162:163], v[146:149], off offset:256 sc1
	s_cbranch_execnz .LBB0_202

; __device__ __forceinline__ unsigned cvt_pk_bf16(float lo, float hi) { unsigned r; asm volatile("v_cvt_pk_bf16_f32 %0, %1, %2" : "=v"(r) : "v"(lo), "v"(hi)); return r; }
;     __device__ __forceinline__ void operator()(const f32x4 (&acc)[2][2][4][2], const Unit& u, int wr, int wc, int fr, int fq) const {
;     ...
;         if (HEADMAJOR && pn < 12) {
;             bf16_t* base; int ct; float sc = 1.f;
;             if (pn < 4) { base = Q; ct = pn; sc = qscale; } else if (pn < 8) { base = Kb; ct = pn - 4; } else { base = V; ct = pn - 8; }
;             const int b = u.pm >> 3, t0 = (u.pm & 7) * BM + wr * 64 + fr;
; #pragma unroll
;             for (int bj = 0; bj < 2; ++bj) { bf16_t* hb = base + ((size_t)((b * 8 + 2 * ct + bj) * 2048 + t0)) * 128 + wc * 32 + 8 * fq;
; #pragma unroll
;                 for (int ai = 0; ai < 2; ++ai)
; #pragma unroll
;                     for (int m = 0; m < 4; ++m) { const f32x4 v0 = acc[ai][bj][m][0] * sc, v1 = acc[ai][bj][m][1] * sc;
;                         u32x4 w; w.x = cvt_pk_bf16(v0[0], v0[1]); w.y = cvt_pk_bf16(v0[2], v0[3]); w.z = cvt_pk_bf16(v1[0], v1[1]); w.w = cvt_pk_bf16(v1[2], v1[3]);
;                         __builtin_nontemporal_store(w, (u32x4*)(hb + (ai * HALF + m * 16) * 128)); } }
.LBB0_223:
	s_lshl_b32 s13, s58, 8
	s_and_b32 s13, s13, 0x700
	s_add_u32 s66, s66, s22
	s_addc_u32 s67, s67, 0
	s_lshl_b32 s33, s58, 11
	s_lshl_b32 s15, s73, 12
	s_and_b32 s33, s33, 0xffffc000
	s_add_i32 s15, s15, s33
	s_or_b32 s13, s15, s13
	v_add_u32_e32 v148, s13, v150
	v_ashrrev_i32_e32 v149, 31, v148
	s_waitcnt lgkmcnt(0)
	v_lshl_add_u64 v[146:147], s[66:67], 0, v[136:137]
	v_lshlrev_b64 v[162:163], 8, v[148:149]
	v_lshl_add_u64 v[162:163], v[146:147], 0, v[162:163]
	v_pk_mul_f32 v[126:127], v[126:127], s[60:61] op_sel_hi:[1,0]
	v_pk_mul_f32 v[124:125], v[124:125], s[60:61] op_sel_hi:[1,0]
	v_pk_mul_f32 v[164:165], v[122:123], s[60:61] op_sel_hi:[1,0]
	v_pk_mul_f32 v[122:123], v[120:121], s[60:61] op_sel_hi:[1,0]
	v_cvt_pk_bf16_f32 v120, v124, v125
	v_cvt_pk_bf16_f32 v121, v126, v127
	v_pk_mul_f32 v[116:117], v[116:117], s[60:61] op_sel_hi:[1,0]
	v_cvt_pk_bf16_f32 v122, v122, v123
	v_cvt_pk_bf16_f32 v123, v164, v165
	global_store_dwordx4 v[162:163], v[120:123], off sc1
	v_pk_mul_f32 v[118:119], v[118:119], s[60:61] op_sel_hi:[1,0]
	v_pk_mul_f32 v[110:111], v[110:111], s[60:61] op_sel_hi:[1,0]
	v_pk_mul_f32 v[120:121], v[114:115], s[60:61] op_sel_hi:[1,0]
	v_pk_mul_f32 v[114:115], v[112:113], s[60:61] op_sel_hi:[1,0]
	v_cvt_pk_bf16_f32 v112, v116, v117
	v_add_co_u32_e32 v116, vcc, s89, v162
	v_cvt_pk_bf16_f32 v113, v118, v119
	v_cvt_pk_bf16_f32 v114, v114, v115
	v_cvt_pk_bf16_f32 v115, v120, v121
	v_pk_mul_f32 v[108:109], v[108:109], s[60:61] op_sel_hi:[1,0]
	s_nop 0
	v_addc_co_u32_e32 v117, vcc, 0, v163, vcc
	global_store_dwordx4 v[116:117], v[112:115], off offset:-4096 sc1
	v_pk_mul_f32 v[100:101], v[100:101], s[60:61] op_sel_hi:[1,0]
	v_pk_mul_f32 v[102:103], v[102:103], s[60:61] op_sel_hi:[1,0]
	v_pk_mul_f32 v[112:113], v[106:107], s[60:61] op_sel_hi:[1,0]
	v_pk_mul_f32 v[106:107], v[104:105], s[60:61] op_sel_hi:[1,0]
	v_cvt_pk_bf16_f32 v104, v108, v109
	v_cvt_pk_bf16_f32 v105, v110, v111
	v_pk_mul_f32 v[92:93], v[92:93], s[60:61] op_sel_hi:[1,0]
	v_cvt_pk_bf16_f32 v106, v106, v107
	v_cvt_pk_bf16_f32 v107, v112, v113
	global_store_dwordx4 v[116:117], v[104:107], off sc1
	v_pk_mul_f32 v[94:95], v[94:95], s[60:61] op_sel_hi:[1,0]
	v_pk_mul_f32 v[86:87], v[86:87], s[60:61] op_sel_hi:[1,0]
	v_pk_mul_f32 v[104:105], v[98:99], s[60:61] op_sel_hi:[1,0]
	v_pk_mul_f32 v[98:99], v[96:97], s[60:61] op_sel_hi:[1,0]
	v_cvt_pk_bf16_f32 v96, v100, v101
	v_add_co_u32_e32 v100, vcc, s23, v162
	v_cvt_pk_bf16_f32 v97, v102, v103
	v_cvt_pk_bf16_f32 v98, v98, v99
	v_cvt_pk_bf16_f32 v99, v104, v105
	v_pk_mul_f32 v[84:85], v[84:85], s[60:61] op_sel_hi:[1,0]
	s_nop 0
	v_addc_co_u32_e32 v101, vcc, 0, v163, vcc
	global_store_dwordx4 v[100:101], v[96:99], off sc1
	v_pk_mul_f32 v[76:77], v[76:77], s[60:61] op_sel_hi:[1,0]
	s_mov_b32 s13, 0xb000
	v_pk_mul_f32 v[96:97], v[90:91], s[60:61] op_sel_hi:[1,0]
	v_pk_mul_f32 v[90:91], v[88:89], s[60:61] op_sel_hi:[1,0]
	v_cvt_pk_bf16_f32 v88, v92, v93
	v_add_co_u32_e32 v92, vcc, s72, v162
	v_cvt_pk_bf16_f32 v89, v94, v95
	v_cvt_pk_bf16_f32 v90, v90, v91
	v_cvt_pk_bf16_f32 v91, v96, v97
	v_pk_mul_f32 v[78:79], v[78:79], s[60:61] op_sel_hi:[1,0]
	s_nop 0
	v_addc_co_u32_e32 v93, vcc, 0, v163, vcc
	global_store_dwordx4 v[92:93], v[88:91], off offset:-4096 sc1
	v_pk_mul_f32 v[60:61], v[60:61], s[60:61] op_sel_hi:[1,0]
	v_pk_mul_f32 v[62:63], v[62:63], s[60:61] op_sel_hi:[1,0]
	v_pk_mul_f32 v[88:89], v[82:83], s[60:61] op_sel_hi:[1,0]
	v_pk_mul_f32 v[82:83], v[80:81], s[60:61] op_sel_hi:[1,0]
	v_cvt_pk_bf16_f32 v80, v84, v85
	v_cvt_pk_bf16_f32 v81, v86, v87
	v_pk_mul_f32 v[64:65], v[64:65], s[60:61] op_sel_hi:[1,0]
	v_cvt_pk_bf16_f32 v82, v82, v83
	v_cvt_pk_bf16_f32 v83, v88, v89
	global_store_dwordx4 v[92:93], v[80:83], off sc1
	v_pk_mul_f32 v[46:47], v[46:47], s[60:61] op_sel_hi:[1,0]
	v_pk_mul_f32 v[44:45], v[44:45], s[60:61] op_sel_hi:[1,0]
	v_pk_mul_f32 v[80:81], v[74:75], s[60:61] op_sel_hi:[1,0]
	v_pk_mul_f32 v[74:75], v[72:73], s[60:61] op_sel_hi:[1,0]
	v_cvt_pk_bf16_f32 v72, v76, v77
	v_add_co_u32_e32 v76, vcc, s13, v162
	v_cvt_pk_bf16_f32 v73, v78, v79
	v_cvt_pk_bf16_f32 v74, v74, v75
	v_cvt_pk_bf16_f32 v75, v80, v81
	v_pk_mul_f32 v[36:37], v[36:37], s[60:61] op_sel_hi:[1,0]
	s_nop 0
	v_addc_co_u32_e32 v77, vcc, 0, v163, vcc
; __device__ __forceinline__ unsigned cvt_pk_bf16(float lo, float hi) { unsigned r; asm volatile("v_cvt_pk_bf16_f32 %0, %1, %2" : "=v"(r) : "v"(lo), "v"(hi)); return r; }
;     __device__ __forceinline__ void operator()(const f32x4 (&acc)[2][2][4][2], const Unit& u, int wr, int wc, int fr, int fq) const {
;     ...
;             for (int bj = 0; bj < 2; ++bj) { bf16_t* hb = base + ((size_t)((b * 8 + 2 * ct + bj) * 2048 + t0)) * 128 + wc * 32 + 8 * fq;
; #pragma unroll
;                 for (int ai = 0; ai < 2; ++ai)
; #pragma unroll
;                     for (int m = 0; m < 4; ++m) { const f32x4 v0 = acc[ai][bj][m][0] * sc, v1 = acc[ai][bj][m][1] * sc;
;                         u32x4 w; w.x = cvt_pk_bf16(v0[0], v0[1]); w.y = cvt_pk_bf16(v0[2], v0[3]); w.z = cvt_pk_bf16(v1[0], v1[1]); w.w = cvt_pk_bf16(v1[2], v1[3]);
;                         __builtin_nontemporal_store(w, (u32x4*)(hb + (ai * HALF + m * 16) * 128)); } }
	global_store_dwordx4 v[76:77], v[72:75], off offset:-4096 sc1
	v_pk_mul_f32 v[38:39], v[38:39], s[60:61] op_sel_hi:[1,0]
	v_pk_mul_f32 v[28:29], v[28:29], s[60:61] op_sel_hi:[1,0]
	v_pk_mul_f32 v[72:73], v[54:55], s[60:61] op_sel_hi:[1,0]
	v_pk_mul_f32 v[54:55], v[52:53], s[60:61] op_sel_hi:[1,0]
	v_cvt_pk_bf16_f32 v52, v60, v61
	v_cvt_pk_bf16_f32 v53, v62, v63
	v_pk_mul_f32 v[62:63], v[66:67], s[60:61] op_sel_hi:[1,0]
	v_cvt_pk_bf16_f32 v54, v54, v55
	v_cvt_pk_bf16_f32 v55, v72, v73
	global_store_dwordx4 v[76:77], v[52:55], off sc1
	v_pk_mul_f32 v[30:31], v[30:31], s[60:61] op_sel_hi:[1,0]
	v_pk_mul_f32 v[22:23], v[22:23], s[60:61] op_sel_hi:[1,0]
	v_add_u32_e32 v52, 0x800, v148
	v_ashrrev_i32_e32 v53, 31, v52
	v_lshlrev_b64 v[52:53], 8, v[52:53]
	v_lshl_add_u64 v[60:61], v[146:147], 0, v[52:53]
	v_pk_mul_f32 v[52:53], v[68:69], s[60:61] op_sel_hi:[1,0]
	v_pk_mul_f32 v[54:55], v[70:71], s[60:61] op_sel_hi:[1,0]
	v_cvt_pk_bf16_f32 v52, v52, v53
	v_pk_mul_f32 v[20:21], v[20:21], s[60:61] op_sel_hi:[1,0]
	v_cvt_pk_bf16_f32 v53, v54, v55
	v_cvt_pk_bf16_f32 v54, v64, v65
	v_cvt_pk_bf16_f32 v55, v62, v63
	global_store_dwordx4 v[60:61], v[52:55], off sc1
	v_pk_mul_f32 v[12:13], v[12:13], s[60:61] op_sel_hi:[1,0]
	s_mov_b32 s13, 0xa000
	v_pk_mul_f32 v[52:53], v[58:59], s[60:61] op_sel_hi:[1,0]
	v_pk_mul_f32 v[54:55], v[56:57], s[60:61] op_sel_hi:[1,0]
	v_pk_mul_f32 v[56:57], v[50:51], s[60:61] op_sel_hi:[1,0]
	v_pk_mul_f32 v[50:51], v[48:49], s[60:61] op_sel_hi:[1,0]
	v_cvt_pk_bf16_f32 v48, v54, v55
	v_cvt_pk_bf16_f32 v49, v52, v53
	v_add_co_u32_e32 v52, vcc, s89, v60
	v_cvt_pk_bf16_f32 v50, v50, v51
	v_cvt_pk_bf16_f32 v51, v56, v57
	v_pk_mul_f32 v[14:15], v[14:15], s[60:61] op_sel_hi:[1,0]
	s_nop 0
	v_addc_co_u32_e32 v53, vcc, 0, v61, vcc
	global_store_dwordx4 v[52:53], v[48:51], off offset:-4096 sc1
	v_pk_mul_f32 v[4:5], v[4:5], s[60:61] op_sel_hi:[1,0]
	v_pk_mul_f32 v[6:7], v[6:7], s[60:61] op_sel_hi:[1,0]
	v_pk_mul_f32 v[48:49], v[42:43], s[60:61] op_sel_hi:[1,0]
	v_pk_mul_f32 v[42:43], v[40:41], s[60:61] op_sel_hi:[1,0]
	v_cvt_pk_bf16_f32 v40, v44, v45
	v_cvt_pk_bf16_f32 v41, v46, v47
	s_nop 0
	v_cvt_pk_bf16_f32 v42, v42, v43
	v_cvt_pk_bf16_f32 v43, v48, v49
	global_store_dwordx4 v[52:53], v[40:43], off sc1
	s_nop 1
	v_pk_mul_f32 v[40:41], v[34:35], s[60:61] op_sel_hi:[1,0]
	v_pk_mul_f32 v[34:35], v[32:33], s[60:61] op_sel_hi:[1,0]
	v_cvt_pk_bf16_f32 v32, v36, v37
	v_add_co_u32_e32 v36, vcc, s23, v60
	v_cvt_pk_bf16_f32 v33, v38, v39
	v_cvt_pk_bf16_f32 v34, v34, v35
	v_cvt_pk_bf16_f32 v35, v40, v41
	s_nop 1
	v_addc_co_u32_e32 v37, vcc, 0, v61, vcc
	global_store_dwordx4 v[36:37], v[32:35], off sc1
	s_nop 1
	v_pk_mul_f32 v[32:33], v[26:27], s[60:61] op_sel_hi:[1,0]
	v_pk_mul_f32 v[26:27], v[24:25], s[60:61] op_sel_hi:[1,0]
	v_cvt_pk_bf16_f32 v24, v28, v29
	v_add_co_u32_e32 v28, vcc, s72, v60
	v_cvt_pk_bf16_f32 v25, v30, v31
	v_cvt_pk_bf16_f32 v26, v26, v27
	v_cvt_pk_bf16_f32 v27, v32, v33
	s_nop 1
	v_addc_co_u32_e32 v29, vcc, 0, v61, vcc
	global_store_dwordx4 v[28:29], v[24:27], off offset:-4096 sc1
	s_nop 1
	v_pk_mul_f32 v[24:25], v[18:19], s[60:61] op_sel_hi:[1,0]
	v_pk_mul_f32 v[18:19], v[16:17], s[60:61] op_sel_hi:[1,0]
	v_cvt_pk_bf16_f32 v16, v20, v21
	v_cvt_pk_bf16_f32 v17, v22, v23
	s_nop 0
	v_cvt_pk_bf16_f32 v18, v18, v19
	v_cvt_pk_bf16_f32 v19, v24, v25
	global_store_dwordx4 v[28:29], v[16:19], off sc1
	s_nop 1
	v_pk_mul_f32 v[16:17], v[10:11], s[60:61] op_sel_hi:[1,0]
	v_pk_mul_f32 v[10:11], v[8:9], s[60:61] op_sel_hi:[1,0]
	v_cvt_pk_bf16_f32 v8, v12, v13
	v_add_co_u32_e32 v12, vcc, s13, v60
	v_cvt_pk_bf16_f32 v9, v14, v15
	v_cvt_pk_bf16_f32 v10, v10, v11
	v_cvt_pk_bf16_f32 v11, v16, v17
	s_nop 1
	v_addc_co_u32_e32 v13, vcc, 0, v61, vcc
	global_store_dwordx4 v[12:13], v[8:11], off sc1
	s_nop 1
	v_pk_mul_f32 v[8:9], v[2:3], s[60:61] op_sel_hi:[1,0]
	v_pk_mul_f32 v[2:3], v[0:1], s[60:61] op_sel_hi:[1,0]
	v_cvt_pk_bf16_f32 v0, v4, v5
	v_add_co_u32_e32 v4, vcc, 0xb000, v60
	v_cvt_pk_bf16_f32 v1, v6, v7
	v_cvt_pk_bf16_f32 v2, v2, v3
	v_cvt_pk_bf16_f32 v3, v8, v9
	s_nop 1
	v_addc_co_u32_e32 v5, vcc, 0, v61, vcc
	global_store_dwordx4 v[4:5], v[0:3], off sc1
	s_andn2_b64 vcc, exec, s[4:5]
	s_mov_b64 s[4:5], -1
	s_cbranch_vccnz .LBB0_193
